# v32_Hnt
# baseline (speedup 1.0000x reference)
; __device__ __forceinline__ unsigned cvt_pk_bf16(float lo, float hi) { unsigned r; asm volatile("v_cvt_pk_bf16_f32 %0, %1, %2" : "=v"(r) : "v"(lo), "v"(hi)); return r; }
; __device__ __forceinline__ float gelu_t(float x) { const float u = 1.5957691216f * (x + 0.044715f * x * x * x); return x * sigm(u); }
; __device__ __forceinline__ float dpp_shr1(float old, float src) { return __int_as_float(__builtin_amdgcn_update_dpp(__float_as_int(old), __float_as_int(src), 0x111, 0xf, 0xf, false)); }
; __device__ __forceinline__ float dpp_shr2(float old, float src) { return __int_as_float(__builtin_amdgcn_update_dpp(__float_as_int(old), __float_as_int(src), 0x112, 0xf, 0xf, false)); }
; __device__ __forceinline__ float dpp_ror1(float src) { return __int_as_float(__builtin_amdgcn_update_dpp(0, __float_as_int(src), 0x121, 0xf, 0xf, false)); }
; __device__ __forceinline__ float dpp_ror2(float src) { return __int_as_float(__builtin_amdgcn_update_dpp(0, __float_as_int(src), 0x122, 0xf, 0xf, false)); }
;     __device__ __forceinline__ void operator()(AccT& acc, const Unit& u, int wr, int wc, int fr, int fq) const {
;     ...
;                 for (int m = 0; m < 4; ++m) {
;                     f32x4 c2[2];
; #pragma unroll
;                     for (int bj = 0; bj < 2; ++bj) { const f32x4 cur = acc[ai][bj][m][n]; const f32x4 pv = (m == 0) ? hv[bj] : acc[ai][bj][m == 0 ? 0 : m - 1][n];
; #pragma unroll
;                         for (int j = 0; j < 4; ++j) { const float p1 = dpp_shr1(dpp_ror1(pv[j]), cur[j]), p2 = dpp_shr2(dpp_ror2(pv[j]), cur[j]);
;                             c2[bj][j] = bia[bj][j] + wgt[bj][0][j] * p2 + wgt[bj][1][j] * p1 + wgt[bj][2][j] * cur[j]; } }
;                     u32x2 w; w.x = cvt_pk_bf16(gelu_t(c2[0][0]) * c2[1][0], gelu_t(c2[0][1]) * c2[1][1]); w.y = cvt_pk_bf16(gelu_t(c2[0][2]) * c2[1][2], gelu_t(c2[0][3]) * c2[1][3]);
;                     if (n == 0) pend[ai][m] = w;
;                     else { u32x4 w4; w4.x = pend[ai][m].x; w4.y = pend[ai][m].y; w4.z = w.x; w4.w = w.y;
;                         *(u32x4*)(F + (size_t)(t0 + ai * 128 + wr * 64 + m * 16 + fr) * FF + cg - 4) = w4; }
.LBB0_792:
	s_or_b64 exec, exec, s[16:17]
	s_waitcnt lgkmcnt(1)
	v_mov_b32_dpp v126, v122 row_ror:2 row_mask:0xf bank_mask:0xf
	s_waitcnt lgkmcnt(0)
	v_mov_b32_dpp v127, v118 row_ror:2 row_mask:0xf bank_mask:0xf
	v_mov_b32_dpp v82, v122 row_ror:1 row_mask:0xf bank_mask:0xf
	v_mov_b32_dpp v126, v60 row_shr:2 row_mask:0xf bank_mask:0xf
	v_mov_b32_dpp v128, v123 row_ror:1 row_mask:0xf bank_mask:0xf
	v_mov_b32_dpp v130, v123 row_ror:2 row_mask:0xf bank_mask:0xf
	v_mov_b32_dpp v83, v118 row_ror:1 row_mask:0xf bank_mask:0xf
	v_mov_b32_dpp v127, v56 row_shr:2 row_mask:0xf bank_mask:0xf
	v_mov_b32_e32 v78, v114
	v_mov_b32_e32 v79, v74
	v_mov_b32_e32 v122, v100
	v_mov_b32_e32 v123, v70
	v_mov_b32_dpp v82, v60 row_shr:1 row_mask:0xf bank_mask:0xf
	v_mov_b32_dpp v134, v124 row_ror:1 row_mask:0xf bank_mask:0xf
	v_mov_b32_dpp v136, v124 row_ror:2 row_mask:0xf bank_mask:0xf
	v_mov_b32_dpp v138, v125 row_ror:1 row_mask:0xf bank_mask:0xf
	v_mov_b32_dpp v140, v125 row_ror:2 row_mask:0xf bank_mask:0xf
	v_mov_b32_dpp v83, v56 row_shr:1 row_mask:0xf bank_mask:0xf
	v_pk_fma_f32 v[126:127], v[78:79], v[126:127], v[122:123]
	v_mov_b32_e32 v124, v110
	v_mov_b32_e32 v125, v84
	v_pk_fma_f32 v[82:83], v[124:125], v[82:83], v[126:127]
	v_mov_b32_e32 v142, v60
	v_mov_b32_e32 v143, v56
	v_mov_b32_e32 v126, v92
	v_mov_b32_e32 v127, v66
	v_mov_b32_dpp v131, v119 row_ror:2 row_mask:0xf bank_mask:0xf
	v_mov_b32_dpp v130, v61 row_shr:2 row_mask:0xf bank_mask:0xf
	v_pk_fma_f32 v[82:83], v[142:143], v[126:127], v[82:83]
	v_mov_b32_dpp v131, v57 row_shr:2 row_mask:0xf bank_mask:0xf
	v_mov_b32_e32 v74, v115
	v_mov_b32_e32 v70, v101
	v_pk_fma_f32 v[100:101], v[74:75], v[130:131], v[70:71]
	v_mov_b32_e32 v131, v68
	v_mul_f32_e32 v68, 0x3d372713, v82
	v_mov_b32_dpp v129, v119 row_ror:1 row_mask:0xf bank_mask:0xf
	v_mul_f32_e32 v68, v82, v68
	v_mov_b32_dpp v128, v61 row_shr:1 row_mask:0xf bank_mask:0xf
	v_mov_b32_dpp v129, v57 row_shr:1 row_mask:0xf bank_mask:0xf
	v_mov_b32_e32 v84, v111
	v_fma_f32 v68, v82, v68, v82
	v_pk_fma_f32 v[100:101], v[84:85], v[128:129], v[100:101]
	v_mov_b32_e32 v110, v61
	v_mov_b32_e32 v111, v57
	v_mov_b32_e32 v66, v93
	v_mul_f32_e32 v68, 0x3fcc422a, v68
	v_pk_fma_f32 v[92:93], v[110:111], v[66:67], v[100:101]
	v_mul_f32_e32 v68, 0xbfb8aa3b, v68
	v_exp_f32_e32 v91, v68
	v_mul_f32_e32 v68, 0x3d372713, v92
	v_mul_f32_e32 v68, v92, v68
	v_fma_f32 v68, v92, v68, v92
	v_mul_f32_e32 v68, 0x3fcc422a, v68
	v_mul_f32_e32 v68, 0xbfb8aa3b, v68
	v_mov_b32_e32 v130, v94
	v_exp_f32_e32 v94, v68
	v_mov_b32_dpp v137, v120 row_ror:2 row_mask:0xf bank_mask:0xf
	v_add_f32_e32 v91, 1.0, v91
	v_mov_b32_dpp v136, v62 row_shr:2 row_mask:0xf bank_mask:0xf
	v_mov_b32_dpp v135, v120 row_ror:1 row_mask:0xf bank_mask:0xf
	v_mov_b32_dpp v137, v58 row_shr:2 row_mask:0xf bank_mask:0xf
	v_mov_b32_e32 v114, v116
	v_mov_b32_e32 v115, v76
	v_mov_b32_e32 v118, v102
	v_mov_b32_e32 v119, v72
	v_mov_b32_dpp v141, v121 row_ror:2 row_mask:0xf bank_mask:0xf
	v_rcp_f32_e32 v91, v91
	v_add_f32_e32 v94, 1.0, v94
	v_mov_b32_dpp v134, v62 row_shr:1 row_mask:0xf bank_mask:0xf
	v_mov_b32_dpp v140, v63 row_shr:2 row_mask:0xf bank_mask:0xf
	v_mov_b32_dpp v135, v58 row_shr:1 row_mask:0xf bank_mask:0xf
	v_pk_fma_f32 v[100:101], v[114:115], v[136:137], v[118:119]
	v_mov_b32_e32 v128, v112
	v_mov_b32_e32 v129, v86
	v_mov_b32_dpp v139, v121 row_ror:1 row_mask:0xf bank_mask:0xf
	v_mov_b32_dpp v141, v59 row_shr:2 row_mask:0xf bank_mask:0xf
	v_mov_b32_e32 v76, v117
	v_mov_b32_e32 v72, v103
	v_rcp_f32_e32 v112, v94
	v_mov_b32_dpp v138, v63 row_shr:1 row_mask:0xf bank_mask:0xf
	v_pk_fma_f32 v[100:101], v[128:129], v[134:135], v[100:101]
	v_mov_b32_e32 v110, v62
	v_mov_b32_e32 v111, v58
	v_mov_b32_dpp v139, v59 row_shr:1 row_mask:0xf bank_mask:0xf
	v_pk_fma_f32 v[102:103], v[76:77], v[140:141], v[72:73]
	v_mov_b32_e32 v86, v113
	v_pk_fma_f32 v[100:101], v[110:111], v[130:131], v[100:101]
	v_pk_fma_f32 v[102:103], v[86:87], v[138:139], v[102:103]
	v_mov_b32_e32 v110, v63
	v_mov_b32_e32 v111, v59
	v_mov_b32_e32 v68, v95
	v_pk_fma_f32 v[94:95], v[110:111], v[68:69], v[102:103]
	v_mul_f32_e32 v82, v82, v91
	v_mul_f32_e32 v82, v82, v83
	v_mul_f32_e32 v83, v92, v112
	v_mul_f32_e32 v91, 0x3d372713, v100
	v_mul_f32_e32 v92, 0x3d372713, v94
	v_mul_f32_e32 v91, v100, v91
	v_mul_f32_e32 v92, v94, v92
	v_fma_f32 v91, v100, v91, v100
	v_fma_f32 v92, v94, v92, v94
	v_mul_f32_e32 v91, 0x3fcc422a, v91
	v_mul_f32_e32 v92, 0x3fcc422a, v92
	v_mul_f32_e32 v91, 0xbfb8aa3b, v91
	v_mul_f32_e32 v92, 0xbfb8aa3b, v92
	v_exp_f32_e32 v91, v91
	v_exp_f32_e32 v92, v92
	v_mul_f32_e32 v83, v83, v93
	s_lshl_b32 s3, s50, 8
	v_add_f32_e32 v91, 1.0, v91
	v_add_f32_e32 v92, 1.0, v92
	v_rcp_f32_e32 v91, v91
	v_rcp_f32_e32 v92, v92
	v_cvt_pk_bf16_f32 v110, v82, v83
	s_add_i32 s3, s3, s76
	v_mul_f32_e32 v82, v100, v91
	v_mul_f32_e32 v83, v94, v92
	v_mul_f32_e32 v82, v82, v101
	v_mul_f32_e32 v83, v83, v95
	v_or_b32_e32 v132, s3, v199
	v_cvt_pk_bf16_f32 v111, v82, v83
	v_mov_b64_e32 v[82:83], s[36:37]
	v_mad_i64_i32 v[92:93], s[8:9], v132, s94, v[82:83]
	v_lshlrev_b64 v[94:95], 1, v[186:187]
	v_lshl_add_u64 v[92:93], v[92:93], 0, v[94:95]
	global_store_dwordx4 v[92:93], v[108:111], off nt
	v_mov_b32_dpp v100, v60 row_ror:2 row_mask:0xf bank_mask:0xf
	v_mov_b32_dpp v101, v56 row_ror:2 row_mask:0xf bank_mask:0xf
	v_mov_b32_dpp v92, v60 row_ror:1 row_mask:0xf bank_mask:0xf
	v_mov_b32_dpp v100, v52 row_shr:2 row_mask:0xf bank_mask:0xf
	v_mov_b32_dpp v108, v62 row_ror:1 row_mask:0xf bank_mask:0xf
	v_mov_b32_dpp v110, v62 row_ror:2 row_mask:0xf bank_mask:0xf
	v_mov_b32_dpp v93, v56 row_ror:1 row_mask:0xf bank_mask:0xf
	v_mov_b32_dpp v101, v48 row_shr:2 row_mask:0xf bank_mask:0xf
; __device__ __forceinline__ unsigned cvt_pk_bf16(float lo, float hi) { unsigned r; asm volatile("v_cvt_pk_bf16_f32 %0, %1, %2" : "=v"(r) : "v"(lo), "v"(hi)); return r; }
; __device__ __forceinline__ float gelu_t(float x) { const float u = 1.5957691216f * (x + 0.044715f * x * x * x); return x * sigm(u); }
; __device__ __forceinline__ float dpp_shr1(float old, float src) { return __int_as_float(__builtin_amdgcn_update_dpp(__float_as_int(old), __float_as_int(src), 0x111, 0xf, 0xf, false)); }
; __device__ __forceinline__ float dpp_shr2(float old, float src) { return __int_as_float(__builtin_amdgcn_update_dpp(__float_as_int(old), __float_as_int(src), 0x112, 0xf, 0xf, false)); }
; __device__ __forceinline__ float dpp_ror1(float src) { return __int_as_float(__builtin_amdgcn_update_dpp(0, __float_as_int(src), 0x121, 0xf, 0xf, false)); }
; __device__ __forceinline__ float dpp_ror2(float src) { return __int_as_float(__builtin_amdgcn_update_dpp(0, __float_as_int(src), 0x122, 0xf, 0xf, false)); }
;     __device__ __forceinline__ void operator()(AccT& acc, const Unit& u, int wr, int wc, int fr, int fq) const {
;     ...
;                 for (int m = 0; m < 4; ++m) {
;                     f32x4 c2[2];
; #pragma unroll
;                     for (int bj = 0; bj < 2; ++bj) { const f32x4 cur = acc[ai][bj][m][n]; const f32x4 pv = (m == 0) ? hv[bj] : acc[ai][bj][m == 0 ? 0 : m - 1][n];
; #pragma unroll
;                         for (int j = 0; j < 4; ++j) { const float p1 = dpp_shr1(dpp_ror1(pv[j]), cur[j]), p2 = dpp_shr2(dpp_ror2(pv[j]), cur[j]);
;                             c2[bj][j] = bia[bj][j] + wgt[bj][0][j] * p2 + wgt[bj][1][j] * p1 + wgt[bj][2][j] * cur[j]; } }
;                     u32x2 w; w.x = cvt_pk_bf16(gelu_t(c2[0][0]) * c2[1][0], gelu_t(c2[0][1]) * c2[1][1]); w.y = cvt_pk_bf16(gelu_t(c2[0][2]) * c2[1][2], gelu_t(c2[0][3]) * c2[1][3]);
;                     if (n == 0) pend[ai][m] = w;
;                     else { u32x4 w4; w4.x = pend[ai][m].x; w4.y = pend[ai][m].y; w4.z = w.x; w4.w = w.y;
;                         *(u32x4*)(F + (size_t)(t0 + ai * 128 + wr * 64 + m * 16 + fr) * FF + cg - 4) = w4; }
	v_mov_b32_dpp v92, v52 row_shr:1 row_mask:0xf bank_mask:0xf
	v_mov_b32_dpp v62, v63 row_ror:1 row_mask:0xf bank_mask:0xf
	v_mov_b32_dpp v112, v63 row_ror:2 row_mask:0xf bank_mask:0xf
	v_mov_b32_dpp v93, v48 row_shr:1 row_mask:0xf bank_mask:0xf
	v_pk_fma_f32 v[100:101], v[78:79], v[100:101], v[122:123]
	v_mov_b32_dpp v113, v59 row_ror:2 row_mask:0xf bank_mask:0xf
	v_mov_b32_dpp v112, v55 row_shr:2 row_mask:0xf bank_mask:0xf
	v_pk_fma_f32 v[92:93], v[124:125], v[92:93], v[100:101]
	v_mov_b32_e32 v100, v52
	v_mov_b32_e32 v101, v48
	v_mov_b32_dpp v63, v59 row_ror:1 row_mask:0xf bank_mask:0xf
	v_mov_b32_dpp v113, v51 row_shr:2 row_mask:0xf bank_mask:0xf
	v_mov_b32_dpp v62, v55 row_shr:1 row_mask:0xf bank_mask:0xf
	v_pk_fma_f32 v[92:93], v[100:101], v[126:127], v[92:93]
	v_mov_b32_dpp v109, v58 row_ror:1 row_mask:0xf bank_mask:0xf
	v_mov_b32_dpp v111, v58 row_ror:2 row_mask:0xf bank_mask:0xf
	v_mov_b32_dpp v63, v51 row_shr:1 row_mask:0xf bank_mask:0xf
	v_pk_fma_f32 v[58:59], v[76:77], v[112:113], v[72:73]
	v_pk_fma_f32 v[58:59], v[86:87], v[62:63], v[58:59]
	v_mul_f32_e32 v63, 0x3d372713, v92
	v_mul_f32_e32 v63, v92, v63
	v_mov_b32_dpp v60, v61 row_ror:1 row_mask:0xf bank_mask:0xf
	v_mov_b32_dpp v102, v61 row_ror:2 row_mask:0xf bank_mask:0xf
	v_mov_b32_dpp v103, v57 row_ror:2 row_mask:0xf bank_mask:0xf
	v_fma_f32 v63, v92, v63, v92
	v_mov_b32_dpp v102, v53 row_shr:2 row_mask:0xf bank_mask:0xf
	v_mov_b32_dpp v61, v57 row_ror:1 row_mask:0xf bank_mask:0xf
	v_mov_b32_dpp v103, v49 row_shr:2 row_mask:0xf bank_mask:0xf
	v_mul_f32_e32 v63, 0x3fcc422a, v63
	v_mov_b32_dpp v60, v53 row_shr:1 row_mask:0xf bank_mask:0xf
	v_mov_b32_dpp v61, v49 row_shr:1 row_mask:0xf bank_mask:0xf
	v_pk_fma_f32 v[56:57], v[74:75], v[102:103], v[70:71]
	v_mul_f32_e32 v63, 0xbfb8aa3b, v63
	v_pk_fma_f32 v[56:57], v[84:85], v[60:61], v[56:57]
	v_mov_b32_e32 v60, v53
	v_mov_b32_e32 v61, v49
	v_exp_f32_e32 v91, v63
	v_pk_fma_f32 v[56:57], v[60:61], v[66:67], v[56:57]
	v_mov_b32_dpp v110, v54 row_shr:2 row_mask:0xf bank_mask:0xf
	v_mul_f32_e32 v63, 0x3d372713, v56
	v_mul_f32_e32 v63, v56, v63
	v_mov_b32_dpp v111, v50 row_shr:2 row_mask:0xf bank_mask:0xf
	v_fma_f32 v63, v56, v63, v56
	v_add_f32_e32 v91, 1.0, v91
	v_mov_b32_dpp v108, v54 row_shr:1 row_mask:0xf bank_mask:0xf
	v_mov_b32_dpp v109, v50 row_shr:1 row_mask:0xf bank_mask:0xf
	v_pk_fma_f32 v[60:61], v[114:115], v[110:111], v[118:119]
	v_mul_f32_e32 v63, 0x3fcc422a, v63
	v_rcp_f32_e32 v91, v91
	v_pk_fma_f32 v[60:61], v[128:129], v[108:109], v[60:61]
	v_mov_b32_e32 v100, v54
	v_mov_b32_e32 v101, v50
	v_mul_f32_e32 v63, 0xbfb8aa3b, v63
	v_pk_fma_f32 v[60:61], v[100:101], v[130:131], v[60:61]
	v_mov_b32_e32 v62, v55
	v_exp_f32_e32 v100, v63
	v_mov_b32_e32 v63, v51
	v_pk_fma_f32 v[58:59], v[62:63], v[68:69], v[58:59]
	v_mul_f32_e32 v63, 0x3d372713, v60
	v_mul_f32_e32 v62, v92, v91
	v_mul_f32_e32 v63, v60, v63
	v_mul_f32_e32 v91, 0x3d372713, v58
	v_fma_f32 v63, v60, v63, v60
	v_mul_f32_e32 v91, v58, v91
	v_add_f32_e32 v100, 1.0, v100
	v_mul_f32_e32 v63, 0x3fcc422a, v63
	v_fma_f32 v91, v58, v91, v58
	v_rcp_f32_e32 v100, v100
	v_mul_f32_e32 v63, 0xbfb8aa3b, v63
	v_mul_f32_e32 v91, 0x3fcc422a, v91
	v_exp_f32_e32 v63, v63
	v_mul_f32_e32 v91, 0xbfb8aa3b, v91
	v_exp_f32_e32 v91, v91
	v_mul_f32_e32 v56, v56, v100
	v_mul_f32_e32 v56, v56, v57
	v_add_f32_e32 v57, 1.0, v63
	v_rcp_f32_e32 v57, v57
	v_add_f32_e32 v63, 1.0, v91
	v_rcp_f32_e32 v63, v63
	v_mul_f32_e32 v62, v62, v93
	v_cvt_pk_bf16_f32 v108, v62, v56
	v_mul_f32_e32 v56, v60, v57
	v_mul_f32_e32 v56, v56, v61
	v_mul_f32_e32 v57, v58, v63
	v_mul_f32_e32 v57, v57, v59
	v_cvt_pk_bf16_f32 v109, v56, v57
	v_or_b32_e32 v56, 16, v132
	v_mad_i64_i32 v[56:57], s[8:9], v56, s94, v[82:83]
	v_lshl_add_u64 v[56:57], v[56:57], 0, v[94:95]
	global_store_dwordx4 v[56:57], v[106:109], off nt
	v_mov_b32_dpp v58, v52 row_ror:2 row_mask:0xf bank_mask:0xf
	v_mov_b32_dpp v59, v48 row_ror:2 row_mask:0xf bank_mask:0xf
	v_mov_b32_dpp v56, v52 row_ror:1 row_mask:0xf bank_mask:0xf
	v_mov_b32_dpp v58, v44 row_shr:2 row_mask:0xf bank_mask:0xf
	v_mov_b32_dpp v62, v54 row_ror:1 row_mask:0xf bank_mask:0xf
	v_mov_b32_dpp v92, v54 row_ror:2 row_mask:0xf bank_mask:0xf
	v_mov_b32_dpp v57, v48 row_ror:1 row_mask:0xf bank_mask:0xf
	v_mov_b32_dpp v59, v40 row_shr:2 row_mask:0xf bank_mask:0xf
	v_mov_b32_dpp v56, v44 row_shr:1 row_mask:0xf bank_mask:0xf
	v_mov_b32_dpp v54, v55 row_ror:1 row_mask:0xf bank_mask:0xf
	v_mov_b32_dpp v100, v55 row_ror:2 row_mask:0xf bank_mask:0xf
	v_mov_b32_dpp v57, v40 row_shr:1 row_mask:0xf bank_mask:0xf
	v_pk_fma_f32 v[58:59], v[78:79], v[58:59], v[122:123]
	v_mov_b32_dpp v101, v51 row_ror:2 row_mask:0xf bank_mask:0xf
	v_mov_b32_dpp v100, v47 row_shr:2 row_mask:0xf bank_mask:0xf
	v_pk_fma_f32 v[56:57], v[124:125], v[56:57], v[58:59]
	v_mov_b32_e32 v58, v44
	v_mov_b32_e32 v59, v40
	v_mov_b32_dpp v55, v51 row_ror:1 row_mask:0xf bank_mask:0xf
	v_mov_b32_dpp v101, v43 row_shr:2 row_mask:0xf bank_mask:0xf
	v_mov_b32_dpp v52, v53 row_ror:1 row_mask:0xf bank_mask:0xf
	v_mov_b32_dpp v60, v53 row_ror:2 row_mask:0xf bank_mask:0xf
	v_mov_b32_dpp v54, v47 row_shr:1 row_mask:0xf bank_mask:0xf
	v_pk_fma_f32 v[56:57], v[58:59], v[126:127], v[56:57]
	v_mov_b32_dpp v61, v49 row_ror:2 row_mask:0xf bank_mask:0xf
	v_mov_b32_dpp v63, v50 row_ror:1 row_mask:0xf bank_mask:0xf
	v_mov_b32_dpp v93, v50 row_ror:2 row_mask:0xf bank_mask:0xf
	v_mov_b32_dpp v55, v43 row_shr:1 row_mask:0xf bank_mask:0xf
	v_pk_fma_f32 v[50:51], v[76:77], v[100:101], v[72:73]
	v_mov_b32_dpp v60, v45 row_shr:2 row_mask:0xf bank_mask:0xf
	v_mov_b32_dpp v53, v49 row_ror:1 row_mask:0xf bank_mask:0xf
	v_mov_b32_dpp v61, v41 row_shr:2 row_mask:0xf bank_mask:0xf
; #define LAS __attribute__((address_space(3)))
; __device__ __forceinline__ unsigned cvt_pk_bf16(float lo, float hi) { unsigned r; asm volatile("v_cvt_pk_bf16_f32 %0, %1, %2" : "=v"(r) : "v"(lo), "v"(hi)); return r; }
; __device__ __forceinline__ float gelu_t(float x) { const float u = 1.5957691216f * (x + 0.044715f * x * x * x); return x * sigm(u); }
; __device__ __forceinline__ float dpp_shr1(float old, float src) { return __int_as_float(__builtin_amdgcn_update_dpp(__float_as_int(old), __float_as_int(src), 0x111, 0xf, 0xf, false)); }
; __device__ __forceinline__ float dpp_shr2(float old, float src) { return __int_as_float(__builtin_amdgcn_update_dpp(__float_as_int(old), __float_as_int(src), 0x112, 0xf, 0xf, false)); }
; __device__ __forceinline__ float dpp_ror1(float src) { return __int_as_float(__builtin_amdgcn_update_dpp(0, __float_as_int(src), 0x121, 0xf, 0xf, false)); }
; __device__ __forceinline__ float dpp_ror2(float src) { return __int_as_float(__builtin_amdgcn_update_dpp(0, __float_as_int(src), 0x122, 0xf, 0xf, false)); }
;     __device__ __forceinline__ void operator()(AccT& acc, const Unit& u, int wr, int wc, int fr, int fq) const {
;     ...
;                 if (has_pred && fr >= 14) { hv[0] = *(const LAS f32x4*)(xl + xidx(pa, pw, wc, fr - 14, fq, 0, n)); hv[1] = *(const LAS f32x4*)(xl + xidx(pa, pw, wc, fr - 14, fq, 1, n)); }
; #pragma unroll
;                 for (int m = 0; m < 4; ++m) {
;                     f32x4 c2[2];
; #pragma unroll
;                     for (int bj = 0; bj < 2; ++bj) { const f32x4 cur = acc[ai][bj][m][n]; const f32x4 pv = (m == 0) ? hv[bj] : acc[ai][bj][m == 0 ? 0 : m - 1][n];
; #pragma unroll
;                         for (int j = 0; j < 4; ++j) { const float p1 = dpp_shr1(dpp_ror1(pv[j]), cur[j]), p2 = dpp_shr2(dpp_ror2(pv[j]), cur[j]);
;                             c2[bj][j] = bia[bj][j] + wgt[bj][0][j] * p2 + wgt[bj][1][j] * p1 + wgt[bj][2][j] * cur[j]; } }
;                     u32x2 w; w.x = cvt_pk_bf16(gelu_t(c2[0][0]) * c2[1][0], gelu_t(c2[0][1]) * c2[1][1]); w.y = cvt_pk_bf16(gelu_t(c2[0][2]) * c2[1][2], gelu_t(c2[0][3]) * c2[1][3]);
;                     if (n == 0) pend[ai][m] = w;
;                     else { u32x4 w4; w4.x = pend[ai][m].x; w4.y = pend[ai][m].y; w4.z = w.x; w4.w = w.y;
;                         *(u32x4*)(F + (size_t)(t0 + ai * 128 + wr * 64 + m * 16 + fr) * FF + cg - 4) = w4; }
	v_pk_fma_f32 v[50:51], v[86:87], v[54:55], v[50:51]
	v_mul_f32_e32 v55, 0x3d372713, v56
	v_mov_b32_dpp v52, v45 row_shr:1 row_mask:0xf bank_mask:0xf
	v_mov_b32_dpp v53, v41 row_shr:1 row_mask:0xf bank_mask:0xf
	v_pk_fma_f32 v[48:49], v[74:75], v[60:61], v[70:71]
	v_mul_f32_e32 v55, v56, v55
	v_mov_b32_dpp v92, v46 row_shr:2 row_mask:0xf bank_mask:0xf
	v_pk_fma_f32 v[48:49], v[84:85], v[52:53], v[48:49]
	v_mov_b32_e32 v52, v45
	v_mov_b32_e32 v53, v41
	v_mov_b32_dpp v93, v42 row_shr:2 row_mask:0xf bank_mask:0xf
	v_fma_f32 v55, v56, v55, v56
	v_mov_b32_dpp v62, v46 row_shr:1 row_mask:0xf bank_mask:0xf
	v_pk_fma_f32 v[48:49], v[52:53], v[66:67], v[48:49]
	v_mov_b32_dpp v63, v42 row_shr:1 row_mask:0xf bank_mask:0xf
	v_pk_fma_f32 v[52:53], v[114:115], v[92:93], v[118:119]
	v_mul_f32_e32 v55, 0x3fcc422a, v55
	v_pk_fma_f32 v[52:53], v[128:129], v[62:63], v[52:53]
	v_mov_b32_e32 v58, v46
	v_mov_b32_e32 v59, v42
	v_mul_f32_e32 v55, 0xbfb8aa3b, v55
	v_pk_fma_f32 v[52:53], v[58:59], v[130:131], v[52:53]
	v_exp_f32_e32 v58, v55
	v_mul_f32_e32 v55, 0x3d372713, v48
	v_mul_f32_e32 v55, v48, v55
	v_fma_f32 v55, v48, v55, v48
	v_add_f32_e32 v58, 1.0, v58
	v_mul_f32_e32 v55, 0x3fcc422a, v55
	v_rcp_f32_e32 v58, v58
	v_mul_f32_e32 v55, 0xbfb8aa3b, v55
	v_mov_b32_e32 v54, v47
	v_exp_f32_e32 v59, v55
	v_mov_b32_e32 v55, v43
	v_pk_fma_f32 v[50:51], v[54:55], v[68:69], v[50:51]
	v_mul_f32_e32 v55, 0x3d372713, v52
	v_mul_f32_e32 v54, v56, v58
	v_mul_f32_e32 v55, v52, v55
	v_mul_f32_e32 v56, 0x3d372713, v50
	v_fma_f32 v55, v52, v55, v52
	v_mul_f32_e32 v56, v50, v56
	v_add_f32_e32 v59, 1.0, v59
	v_mul_f32_e32 v55, 0x3fcc422a, v55
	v_fma_f32 v56, v50, v56, v50
	v_rcp_f32_e32 v59, v59
	v_mul_f32_e32 v55, 0xbfb8aa3b, v55
	v_mul_f32_e32 v56, 0x3fcc422a, v56
	v_exp_f32_e32 v55, v55
	v_mul_f32_e32 v56, 0xbfb8aa3b, v56
	v_exp_f32_e32 v56, v56
	v_mul_f32_e32 v48, v48, v59
	v_mul_f32_e32 v48, v48, v49
	v_add_f32_e32 v49, 1.0, v55
	v_rcp_f32_e32 v49, v49
	v_add_f32_e32 v55, 1.0, v56
	v_rcp_f32_e32 v55, v55
	v_mul_f32_e32 v54, v54, v57
	v_cvt_pk_bf16_f32 v106, v54, v48
	v_mul_f32_e32 v48, v52, v49
	v_mul_f32_e32 v48, v48, v53
	v_mul_f32_e32 v49, v50, v55
	v_mul_f32_e32 v49, v49, v51
	v_cvt_pk_bf16_f32 v107, v48, v49
	v_or_b32_e32 v48, 32, v132
	v_mad_i64_i32 v[48:49], s[8:9], v48, s94, v[82:83]
	v_lshl_add_u64 v[48:49], v[48:49], 0, v[94:95]
	global_store_dwordx4 v[48:49], v[104:107], off nt
	v_mov_b32_dpp v48, v44 row_ror:1 row_mask:0xf bank_mask:0xf
	v_mov_b32_dpp v50, v44 row_ror:2 row_mask:0xf bank_mask:0xf
	v_mov_b32_dpp v51, v40 row_ror:2 row_mask:0xf bank_mask:0xf
	v_mov_b32_dpp v50, v36 row_shr:2 row_mask:0xf bank_mask:0xf
	v_mov_b32_dpp v44, v45 row_ror:1 row_mask:0xf bank_mask:0xf
	v_mov_b32_dpp v52, v45 row_ror:2 row_mask:0xf bank_mask:0xf
	v_mov_b32_dpp v49, v40 row_ror:1 row_mask:0xf bank_mask:0xf
	v_mov_b32_dpp v51, v32 row_shr:2 row_mask:0xf bank_mask:0xf
	v_mov_b32_dpp v53, v41 row_ror:2 row_mask:0xf bank_mask:0xf
	v_mov_b32_dpp v48, v36 row_shr:1 row_mask:0xf bank_mask:0xf
	v_mov_b32_dpp v52, v37 row_shr:2 row_mask:0xf bank_mask:0xf
	v_mov_b32_dpp v49, v32 row_shr:1 row_mask:0xf bank_mask:0xf
	v_pk_fma_f32 v[50:51], v[78:79], v[50:51], v[122:123]
	v_mov_b32_dpp v45, v41 row_ror:1 row_mask:0xf bank_mask:0xf
	v_mov_b32_dpp v53, v33 row_shr:2 row_mask:0xf bank_mask:0xf
	v_mov_b32_dpp v44, v37 row_shr:1 row_mask:0xf bank_mask:0xf
	v_pk_fma_f32 v[48:49], v[124:125], v[48:49], v[50:51]
	v_mov_b32_e32 v50, v36
	v_mov_b32_e32 v51, v32
	v_mov_b32_dpp v45, v33 row_shr:1 row_mask:0xf bank_mask:0xf
	v_pk_fma_f32 v[40:41], v[74:75], v[52:53], v[70:71]
	v_pk_fma_f32 v[48:49], v[50:51], v[126:127], v[48:49]
	v_pk_fma_f32 v[40:41], v[84:85], v[44:45], v[40:41]
	v_mov_b32_e32 v32, v37
	v_mov_b32_dpp v55, v42 row_ror:1 row_mask:0xf bank_mask:0xf
	v_mov_b32_dpp v57, v42 row_ror:2 row_mask:0xf bank_mask:0xf
	v_pk_fma_f32 v[32:33], v[32:33], v[66:67], v[40:41]
	v_mov_b32_dpp v55, v34 row_shr:1 row_mask:0xf bank_mask:0xf
	v_mov_b32_dpp v57, v34 row_shr:2 row_mask:0xf bank_mask:0xf
	v_mov_b32_e32 v41, v34
	v_mul_f32_e32 v34, 0x3d372713, v48
	v_mul_f32_e32 v34, v48, v34
	v_fma_f32 v34, v48, v34, v48
	v_mul_f32_e32 v34, 0x3fcc422a, v34
	v_mov_b32_dpp v54, v46 row_ror:1 row_mask:0xf bank_mask:0xf
	v_mov_b32_dpp v56, v46 row_ror:2 row_mask:0xf bank_mask:0xf
	v_mul_f32_e32 v34, 0xbfb8aa3b, v34
	v_mov_b32_dpp v54, v38 row_shr:1 row_mask:0xf bank_mask:0xf
	v_mov_b32_dpp v56, v38 row_shr:2 row_mask:0xf bank_mask:0xf
	v_mov_b32_e32 v40, v38
	v_exp_f32_e32 v38, v34
	v_mul_f32_e32 v34, 0x3d372713, v32
	v_mul_f32_e32 v34, v32, v34
	v_fma_f32 v34, v32, v34, v32
	v_mul_f32_e32 v34, 0x3fcc422a, v34
	v_mul_f32_e32 v34, 0xbfb8aa3b, v34
	v_exp_f32_e32 v42, v34
	v_mov_b32_dpp v46, v47 row_ror:1 row_mask:0xf bank_mask:0xf
	v_mov_b32_dpp v58, v47 row_ror:2 row_mask:0xf bank_mask:0xf
	v_mov_b32_e32 v34, v39
	v_mov_b32_dpp v46, v39 row_shr:1 row_mask:0xf bank_mask:0xf
	v_mov_b32_dpp v58, v39 row_shr:2 row_mask:0xf bank_mask:0xf
	v_add_f32_e32 v39, 1.0, v42
	v_pk_fma_f32 v[36:37], v[114:115], v[56:57], v[118:119]
	v_mov_b32_dpp v59, v43 row_ror:2 row_mask:0xf bank_mask:0xf
	v_rcp_f32_e32 v39, v39
	v_pk_fma_f32 v[36:37], v[128:129], v[54:55], v[36:37]
	v_mov_b32_dpp v47, v43 row_ror:1 row_mask:0xf bank_mask:0xf
	v_mov_b32_dpp v59, v35 row_shr:2 row_mask:0xf bank_mask:0xf
	v_pk_fma_f32 v[36:37], v[40:41], v[130:131], v[36:37]
	v_mov_b32_dpp v47, v35 row_shr:1 row_mask:0xf bank_mask:0xf
	v_pk_fma_f32 v[40:41], v[76:77], v[58:59], v[72:73]
	v_mul_f32_e32 v32, v32, v39
	v_pk_fma_f32 v[40:41], v[86:87], v[46:47], v[40:41]
	v_mul_f32_e32 v39, 0x3d372713, v36
	v_pk_fma_f32 v[34:35], v[34:35], v[68:69], v[40:41]
	v_mul_f32_e32 v39, v36, v39
	v_mul_f32_e32 v40, 0x3d372713, v34
	v_fma_f32 v39, v36, v39, v36
	v_mul_f32_e32 v40, v34, v40
	v_mul_f32_e32 v39, 0x3fcc422a, v39
	v_fma_f32 v40, v34, v40, v34
	v_mul_f32_e32 v39, 0xbfb8aa3b, v39
	v_mul_f32_e32 v40, 0x3fcc422a, v40
	v_exp_f32_e32 v39, v39
	v_mul_f32_e32 v40, 0xbfb8aa3b, v40
	v_exp_f32_e32 v40, v40
	v_add_f32_e32 v38, 1.0, v38
	v_rcp_f32_e32 v38, v38
	v_mul_f32_e32 v32, v32, v33
	v_add_f32_e32 v33, 1.0, v39
	v_rcp_f32_e32 v33, v33
	v_add_f32_e32 v39, 1.0, v40
	v_rcp_f32_e32 v39, v39
	v_mul_f32_e32 v38, v48, v38
	v_mul_f32_e32 v38, v38, v49
	v_cvt_pk_bf16_f32 v100, v38, v32
	v_mul_f32_e32 v32, v36, v33
	v_mul_f32_e32 v32, v32, v37
	v_mul_f32_e32 v33, v34, v39
	v_mul_f32_e32 v33, v33, v35
	v_cvt_pk_bf16_f32 v101, v32, v33
	v_or_b32_e32 v32, 48, v132
	v_mad_i64_i32 v[32:33], s[8:9], v32, s94, v[82:83]
	v_lshl_add_u64 v[32:33], v[32:33], 0, v[94:95]
	global_store_dwordx4 v[32:33], v[98:101], off nt
	v_mov_b32_e32 v91, 0
	v_mov_b32_e32 v92, 0
	v_mov_b32_e32 v93, 0
	v_mov_b32_e32 v32, 0
	v_mov_b32_e32 v33, 0
	v_mov_b32_e32 v34, 0
	v_mov_b32_e32 v35, 0
	s_and_saveexec_b64 s[12:13], s[6:7]
	s_cbranch_execz .LBB0_794
	ds_read_b128 v[32:35], v154 offset:16
	ds_read_b128 v[90:93], v154 offset:48
; __device__ __forceinline__ unsigned cvt_pk_bf16(float lo, float hi) { unsigned r; asm volatile("v_cvt_pk_bf16_f32 %0, %1, %2" : "=v"(r) : "v"(lo), "v"(hi)); return r; }
; __device__ __forceinline__ float gelu_t(float x) { const float u = 1.5957691216f * (x + 0.044715f * x * x * x); return x * sigm(u); }
; __device__ __forceinline__ float dpp_shr1(float old, float src) { return __int_as_float(__builtin_amdgcn_update_dpp(__float_as_int(old), __float_as_int(src), 0x111, 0xf, 0xf, false)); }
; __device__ __forceinline__ float dpp_shr2(float old, float src) { return __int_as_float(__builtin_amdgcn_update_dpp(__float_as_int(old), __float_as_int(src), 0x112, 0xf, 0xf, false)); }
; __device__ __forceinline__ float dpp_ror1(float src) { return __int_as_float(__builtin_amdgcn_update_dpp(0, __float_as_int(src), 0x121, 0xf, 0xf, false)); }
; __device__ __forceinline__ float dpp_ror2(float src) { return __int_as_float(__builtin_amdgcn_update_dpp(0, __float_as_int(src), 0x122, 0xf, 0xf, false)); }
;     __device__ __forceinline__ void operator()(AccT& acc, const Unit& u, int wr, int wc, int fr, int fq) const {
;     ...
;                 for (int m = 0; m < 4; ++m) {
;                     f32x4 c2[2];
; #pragma unroll
;                     for (int bj = 0; bj < 2; ++bj) { const f32x4 cur = acc[ai][bj][m][n]; const f32x4 pv = (m == 0) ? hv[bj] : acc[ai][bj][m == 0 ? 0 : m - 1][n];
; #pragma unroll
;                         for (int j = 0; j < 4; ++j) { const float p1 = dpp_shr1(dpp_ror1(pv[j]), cur[j]), p2 = dpp_shr2(dpp_ror2(pv[j]), cur[j]);
;                             c2[bj][j] = bia[bj][j] + wgt[bj][0][j] * p2 + wgt[bj][1][j] * p1 + wgt[bj][2][j] * cur[j]; } }
;                     u32x2 w; w.x = cvt_pk_bf16(gelu_t(c2[0][0]) * c2[1][0], gelu_t(c2[0][1]) * c2[1][1]); w.y = cvt_pk_bf16(gelu_t(c2[0][2]) * c2[1][2], gelu_t(c2[0][3]) * c2[1][3]);
;                     if (n == 0) pend[ai][m] = w;
;                     else { u32x4 w4; w4.x = pend[ai][m].x; w4.y = pend[ai][m].y; w4.z = w.x; w4.w = w.y;
;                         *(u32x4*)(F + (size_t)(t0 + ai * 128 + wr * 64 + m * 16 + fr) * FF + cg - 4) = w4; }
.LBB0_794:
	s_or_b64 exec, exec, s[12:13]
	s_waitcnt lgkmcnt(1)
	v_mov_b32_dpp v38, v32 row_ror:2 row_mask:0xf bank_mask:0xf
	s_waitcnt lgkmcnt(0)
	v_mov_b32_dpp v39, v90 row_ror:2 row_mask:0xf bank_mask:0xf
	v_mov_b32_dpp v36, v32 row_ror:1 row_mask:0xf bank_mask:0xf
	v_mov_b32_dpp v38, v28 row_shr:2 row_mask:0xf bank_mask:0xf
	v_mov_b32_dpp v37, v90 row_ror:1 row_mask:0xf bank_mask:0xf
	v_mov_b32_dpp v39, v24 row_shr:2 row_mask:0xf bank_mask:0xf
	v_mov_b32_dpp v36, v28 row_shr:1 row_mask:0xf bank_mask:0xf
	v_mov_b32_dpp v32, v33 row_ror:1 row_mask:0xf bank_mask:0xf
	v_mov_b32_dpp v40, v33 row_ror:2 row_mask:0xf bank_mask:0xf
	v_mov_b32_dpp v37, v24 row_shr:1 row_mask:0xf bank_mask:0xf
	v_pk_fma_f32 v[38:39], v[78:79], v[38:39], v[122:123]
	v_mov_b32_dpp v41, v91 row_ror:2 row_mask:0xf bank_mask:0xf
	v_mov_b32_dpp v40, v29 row_shr:2 row_mask:0xf bank_mask:0xf
	v_pk_fma_f32 v[36:37], v[124:125], v[36:37], v[38:39]
	v_mov_b32_e32 v38, v28
	v_mov_b32_e32 v39, v24
	v_mov_b32_dpp v33, v91 row_ror:1 row_mask:0xf bank_mask:0xf
	v_mov_b32_dpp v41, v25 row_shr:2 row_mask:0xf bank_mask:0xf
	v_mov_b32_dpp v32, v29 row_shr:1 row_mask:0xf bank_mask:0xf
	v_mov_b32_dpp v44, v34 row_ror:2 row_mask:0xf bank_mask:0xf
	v_pk_fma_f32 v[36:37], v[38:39], v[126:127], v[36:37]
	v_mov_b32_dpp v33, v25 row_shr:1 row_mask:0xf bank_mask:0xf
	v_pk_fma_f32 v[38:39], v[74:75], v[40:41], v[70:71]
	v_mov_b32_dpp v45, v92 row_ror:2 row_mask:0xf bank_mask:0xf
	v_mov_b32_dpp v42, v34 row_ror:1 row_mask:0xf bank_mask:0xf
	v_mov_b32_dpp v44, v30 row_shr:2 row_mask:0xf bank_mask:0xf
	v_pk_fma_f32 v[32:33], v[84:85], v[32:33], v[38:39]
	v_mov_b32_e32 v38, v29
	v_mov_b32_e32 v39, v25
	v_mov_b32_dpp v43, v92 row_ror:1 row_mask:0xf bank_mask:0xf
	v_mov_b32_dpp v45, v26 row_shr:2 row_mask:0xf bank_mask:0xf
	v_mov_b32_dpp v42, v30 row_shr:1 row_mask:0xf bank_mask:0xf
	v_mov_b32_dpp v34, v35 row_ror:1 row_mask:0xf bank_mask:0xf
	v_mov_b32_dpp v46, v35 row_ror:2 row_mask:0xf bank_mask:0xf
	v_pk_fma_f32 v[32:33], v[38:39], v[66:67], v[32:33]
	v_mov_b32_dpp v43, v26 row_shr:1 row_mask:0xf bank_mask:0xf
	v_pk_fma_f32 v[38:39], v[114:115], v[44:45], v[118:119]
	v_mov_b32_dpp v47, v93 row_ror:2 row_mask:0xf bank_mask:0xf
	v_mov_b32_dpp v46, v31 row_shr:2 row_mask:0xf bank_mask:0xf
	v_pk_fma_f32 v[38:39], v[128:129], v[42:43], v[38:39]
	v_mov_b32_e32 v40, v30
	v_mov_b32_e32 v41, v26
	v_mov_b32_dpp v35, v93 row_ror:1 row_mask:0xf bank_mask:0xf
	v_mov_b32_dpp v47, v27 row_shr:2 row_mask:0xf bank_mask:0xf
	v_mov_b32_dpp v34, v31 row_shr:1 row_mask:0xf bank_mask:0xf
	v_pk_fma_f32 v[38:39], v[40:41], v[130:131], v[38:39]
	v_mov_b32_dpp v35, v27 row_shr:1 row_mask:0xf bank_mask:0xf
	v_pk_fma_f32 v[40:41], v[76:77], v[46:47], v[72:73]
	v_add_u32_e32 v48, 0x80, v132
	v_pk_fma_f32 v[34:35], v[86:87], v[34:35], v[40:41]
	v_mul_f32_e32 v41, 0x3d372713, v36
	v_mul_f32_e32 v41, v36, v41
	v_fma_f32 v41, v36, v41, v36
	v_mul_f32_e32 v41, 0x3fcc422a, v41
	v_mul_f32_e32 v41, 0xbfb8aa3b, v41
	v_exp_f32_e32 v42, v41
	v_mul_f32_e32 v41, 0x3d372713, v32
	v_mul_f32_e32 v41, v32, v41
	v_fma_f32 v41, v32, v41, v32
	v_add_f32_e32 v42, 1.0, v42
	v_rcp_f32_e32 v42, v42
	v_mul_f32_e32 v41, 0x3fcc422a, v41
	v_mul_f32_e32 v41, 0xbfb8aa3b, v41
	v_mov_b32_e32 v40, v31
	v_exp_f32_e32 v43, v41
	v_mov_b32_e32 v41, v27
	v_pk_fma_f32 v[34:35], v[40:41], v[68:69], v[34:35]
	v_mul_f32_e32 v36, v36, v42
	v_mul_f32_e32 v36, v36, v37
	v_mul_f32_e32 v37, 0x3d372713, v38
	v_mul_f32_e32 v40, 0x3d372713, v34
	v_mul_f32_e32 v37, v38, v37
	v_mul_f32_e32 v40, v34, v40
	v_fma_f32 v37, v38, v37, v38
	v_fma_f32 v40, v34, v40, v34
	v_add_f32_e32 v43, 1.0, v43
	v_mul_f32_e32 v37, 0x3fcc422a, v37
	v_mul_f32_e32 v40, 0x3fcc422a, v40
	v_rcp_f32_e32 v43, v43
	v_mul_f32_e32 v37, 0xbfb8aa3b, v37
	v_mul_f32_e32 v40, 0xbfb8aa3b, v40
	v_exp_f32_e32 v37, v37
	v_exp_f32_e32 v40, v40
	v_mul_f32_e32 v32, v32, v43
	v_mul_f32_e32 v32, v32, v33
	v_add_f32_e32 v33, 1.0, v37
	v_add_f32_e32 v37, 1.0, v40
	v_rcp_f32_e32 v33, v33
	v_rcp_f32_e32 v37, v37
	v_cvt_pk_bf16_f32 v98, v36, v32
	v_mul_f32_e32 v32, v38, v33
	v_mul_f32_e32 v33, v34, v37
	v_mul_f32_e32 v32, v32, v39
	v_mul_f32_e32 v33, v33, v35
	v_cvt_pk_bf16_f32 v99, v32, v33
	v_mov_b64_e32 v[32:33], s[36:37]
	v_mad_i64_i32 v[34:35], s[6:7], v48, s94, v[32:33]
	v_lshl_add_u64 v[34:35], v[34:35], 0, v[94:95]
	global_store_dwordx4 v[34:35], v[96:99], off nt
	v_mov_b32_dpp v36, v28 row_ror:2 row_mask:0xf bank_mask:0xf
	v_mov_b32_dpp v37, v24 row_ror:2 row_mask:0xf bank_mask:0xf
	v_mov_b32_dpp v34, v28 row_ror:1 row_mask:0xf bank_mask:0xf
	v_mov_b32_dpp v36, v20 row_shr:2 row_mask:0xf bank_mask:0xf
	v_mov_b32_dpp v40, v30 row_ror:1 row_mask:0xf bank_mask:0xf
	v_mov_b32_dpp v42, v30 row_ror:2 row_mask:0xf bank_mask:0xf
	v_mov_b32_dpp v35, v24 row_ror:1 row_mask:0xf bank_mask:0xf
	v_mov_b32_dpp v37, v16 row_shr:2 row_mask:0xf bank_mask:0xf
	v_mov_b32_dpp v34, v20 row_shr:1 row_mask:0xf bank_mask:0xf
	v_mov_b32_dpp v30, v31 row_ror:1 row_mask:0xf bank_mask:0xf
	v_mov_b32_dpp v44, v31 row_ror:2 row_mask:0xf bank_mask:0xf
	v_mov_b32_dpp v35, v16 row_shr:1 row_mask:0xf bank_mask:0xf
	v_pk_fma_f32 v[36:37], v[78:79], v[36:37], v[122:123]
	v_mov_b32_dpp v45, v27 row_ror:2 row_mask:0xf bank_mask:0xf
	v_mov_b32_dpp v44, v23 row_shr:2 row_mask:0xf bank_mask:0xf
	v_pk_fma_f32 v[34:35], v[124:125], v[34:35], v[36:37]
	v_mov_b32_e32 v36, v20
	v_mov_b32_e32 v37, v16
	v_mov_b32_dpp v31, v27 row_ror:1 row_mask:0xf bank_mask:0xf
	v_mov_b32_dpp v45, v19 row_shr:2 row_mask:0xf bank_mask:0xf
	v_mov_b32_dpp v28, v29 row_ror:1 row_mask:0xf bank_mask:0xf
	v_mov_b32_dpp v38, v29 row_ror:2 row_mask:0xf bank_mask:0xf
; __device__ __forceinline__ unsigned cvt_pk_bf16(float lo, float hi) { unsigned r; asm volatile("v_cvt_pk_bf16_f32 %0, %1, %2" : "=v"(r) : "v"(lo), "v"(hi)); return r; }
; __device__ __forceinline__ float gelu_t(float x) { const float u = 1.5957691216f * (x + 0.044715f * x * x * x); return x * sigm(u); }
; __device__ __forceinline__ float dpp_shr1(float old, float src) { return __int_as_float(__builtin_amdgcn_update_dpp(__float_as_int(old), __float_as_int(src), 0x111, 0xf, 0xf, false)); }
; __device__ __forceinline__ float dpp_shr2(float old, float src) { return __int_as_float(__builtin_amdgcn_update_dpp(__float_as_int(old), __float_as_int(src), 0x112, 0xf, 0xf, false)); }
; __device__ __forceinline__ float dpp_ror1(float src) { return __int_as_float(__builtin_amdgcn_update_dpp(0, __float_as_int(src), 0x121, 0xf, 0xf, false)); }
; __device__ __forceinline__ float dpp_ror2(float src) { return __int_as_float(__builtin_amdgcn_update_dpp(0, __float_as_int(src), 0x122, 0xf, 0xf, false)); }
;     __device__ __forceinline__ void operator()(AccT& acc, const Unit& u, int wr, int wc, int fr, int fq) const {
;     ...
;                 for (int m = 0; m < 4; ++m) {
;                     f32x4 c2[2];
; #pragma unroll
;                     for (int bj = 0; bj < 2; ++bj) { const f32x4 cur = acc[ai][bj][m][n]; const f32x4 pv = (m == 0) ? hv[bj] : acc[ai][bj][m == 0 ? 0 : m - 1][n];
; #pragma unroll
;                         for (int j = 0; j < 4; ++j) { const float p1 = dpp_shr1(dpp_ror1(pv[j]), cur[j]), p2 = dpp_shr2(dpp_ror2(pv[j]), cur[j]);
;                             c2[bj][j] = bia[bj][j] + wgt[bj][0][j] * p2 + wgt[bj][1][j] * p1 + wgt[bj][2][j] * cur[j]; } }
;                     u32x2 w; w.x = cvt_pk_bf16(gelu_t(c2[0][0]) * c2[1][0], gelu_t(c2[0][1]) * c2[1][1]); w.y = cvt_pk_bf16(gelu_t(c2[0][2]) * c2[1][2], gelu_t(c2[0][3]) * c2[1][3]);
;                     if (n == 0) pend[ai][m] = w;
;                     else { u32x4 w4; w4.x = pend[ai][m].x; w4.y = pend[ai][m].y; w4.z = w.x; w4.w = w.y;
;                         *(u32x4*)(F + (size_t)(t0 + ai * 128 + wr * 64 + m * 16 + fr) * FF + cg - 4) = w4; }
	v_mov_b32_dpp v30, v23 row_shr:1 row_mask:0xf bank_mask:0xf
	v_pk_fma_f32 v[34:35], v[36:37], v[126:127], v[34:35]
	v_mov_b32_dpp v39, v25 row_ror:2 row_mask:0xf bank_mask:0xf
	v_mov_b32_dpp v41, v26 row_ror:1 row_mask:0xf bank_mask:0xf
	v_mov_b32_dpp v43, v26 row_ror:2 row_mask:0xf bank_mask:0xf
	v_mov_b32_dpp v31, v19 row_shr:1 row_mask:0xf bank_mask:0xf
	v_pk_fma_f32 v[26:27], v[76:77], v[44:45], v[72:73]
	v_mov_b32_dpp v38, v21 row_shr:2 row_mask:0xf bank_mask:0xf
	v_mov_b32_dpp v29, v25 row_ror:1 row_mask:0xf bank_mask:0xf
	v_mov_b32_dpp v39, v17 row_shr:2 row_mask:0xf bank_mask:0xf
	v_pk_fma_f32 v[26:27], v[86:87], v[30:31], v[26:27]
	v_mul_f32_e32 v31, 0x3d372713, v34
	v_mov_b32_dpp v28, v21 row_shr:1 row_mask:0xf bank_mask:0xf
	v_mov_b32_dpp v29, v17 row_shr:1 row_mask:0xf bank_mask:0xf
	v_pk_fma_f32 v[24:25], v[74:75], v[38:39], v[70:71]
	v_mul_f32_e32 v31, v34, v31
	v_mov_b32_dpp v42, v22 row_shr:2 row_mask:0xf bank_mask:0xf
	v_pk_fma_f32 v[24:25], v[84:85], v[28:29], v[24:25]
	v_mov_b32_e32 v28, v21
	v_mov_b32_e32 v29, v17
	v_mov_b32_dpp v43, v18 row_shr:2 row_mask:0xf bank_mask:0xf
	v_fma_f32 v31, v34, v31, v34
	v_mov_b32_dpp v40, v22 row_shr:1 row_mask:0xf bank_mask:0xf
	v_pk_fma_f32 v[24:25], v[28:29], v[66:67], v[24:25]
	v_mov_b32_dpp v41, v18 row_shr:1 row_mask:0xf bank_mask:0xf
	v_pk_fma_f32 v[28:29], v[114:115], v[42:43], v[118:119]
	v_mul_f32_e32 v31, 0x3fcc422a, v31
	v_pk_fma_f32 v[28:29], v[128:129], v[40:41], v[28:29]
	v_mov_b32_e32 v36, v22
	v_mov_b32_e32 v37, v18
	v_mul_f32_e32 v31, 0xbfb8aa3b, v31
	v_pk_fma_f32 v[28:29], v[36:37], v[130:131], v[28:29]
	v_exp_f32_e32 v36, v31
	v_mul_f32_e32 v31, 0x3d372713, v24
	v_mul_f32_e32 v31, v24, v31
	v_fma_f32 v31, v24, v31, v24
	v_add_f32_e32 v36, 1.0, v36
	v_mul_f32_e32 v31, 0x3fcc422a, v31
	v_rcp_f32_e32 v36, v36
	v_mul_f32_e32 v31, 0xbfb8aa3b, v31
	v_mov_b32_e32 v30, v23
	v_exp_f32_e32 v37, v31
	v_mov_b32_e32 v31, v19
	v_pk_fma_f32 v[26:27], v[30:31], v[68:69], v[26:27]
	v_mul_f32_e32 v31, 0x3d372713, v28
	v_mul_f32_e32 v30, v34, v36
	v_mul_f32_e32 v31, v28, v31
	v_mul_f32_e32 v34, 0x3d372713, v26
	v_fma_f32 v31, v28, v31, v28
	v_mul_f32_e32 v34, v26, v34
	v_add_f32_e32 v37, 1.0, v37
	v_mul_f32_e32 v31, 0x3fcc422a, v31
	v_fma_f32 v34, v26, v34, v26
	v_rcp_f32_e32 v37, v37
	v_mul_f32_e32 v31, 0xbfb8aa3b, v31
	v_mul_f32_e32 v34, 0x3fcc422a, v34
	v_exp_f32_e32 v31, v31
	v_mul_f32_e32 v34, 0xbfb8aa3b, v34
	v_exp_f32_e32 v34, v34
	v_mul_f32_e32 v24, v24, v37
	v_mul_f32_e32 v24, v24, v25
	v_add_f32_e32 v25, 1.0, v31
	v_rcp_f32_e32 v25, v25
	v_add_f32_e32 v31, 1.0, v34
	v_rcp_f32_e32 v31, v31
	v_mul_f32_e32 v30, v30, v35
	v_cvt_pk_bf16_f32 v90, v30, v24
	v_mul_f32_e32 v24, v28, v25
	v_mul_f32_e32 v24, v24, v29
	v_mul_f32_e32 v25, v26, v31
	v_mul_f32_e32 v25, v25, v27
	v_cvt_pk_bf16_f32 v91, v24, v25
	v_add_u32_e32 v24, 0x90, v132
	v_mad_i64_i32 v[24:25], s[6:7], v24, s94, v[32:33]
	v_lshl_add_u64 v[24:25], v[24:25], 0, v[94:95]
	global_store_dwordx4 v[24:25], v[88:91], off nt
	v_mov_b32_dpp v26, v20 row_ror:2 row_mask:0xf bank_mask:0xf
	v_mov_b32_dpp v27, v16 row_ror:2 row_mask:0xf bank_mask:0xf
	v_mov_b32_dpp v24, v20 row_ror:1 row_mask:0xf bank_mask:0xf
	v_mov_b32_dpp v26, v12 row_shr:2 row_mask:0xf bank_mask:0xf
	v_mov_b32_dpp v30, v22 row_ror:1 row_mask:0xf bank_mask:0xf
	v_mov_b32_dpp v34, v22 row_ror:2 row_mask:0xf bank_mask:0xf
	v_mov_b32_dpp v25, v16 row_ror:1 row_mask:0xf bank_mask:0xf
	v_mov_b32_dpp v27, v8 row_shr:2 row_mask:0xf bank_mask:0xf
	v_mov_b32_dpp v24, v12 row_shr:1 row_mask:0xf bank_mask:0xf
	v_mov_b32_dpp v22, v23 row_ror:1 row_mask:0xf bank_mask:0xf
	v_mov_b32_dpp v36, v23 row_ror:2 row_mask:0xf bank_mask:0xf
	v_mov_b32_dpp v25, v8 row_shr:1 row_mask:0xf bank_mask:0xf
	v_pk_fma_f32 v[26:27], v[78:79], v[26:27], v[122:123]
	v_mov_b32_dpp v37, v19 row_ror:2 row_mask:0xf bank_mask:0xf
	v_mov_b32_dpp v36, v15 row_shr:2 row_mask:0xf bank_mask:0xf
	v_pk_fma_f32 v[24:25], v[124:125], v[24:25], v[26:27]
	v_mov_b32_e32 v26, v12
	v_mov_b32_e32 v27, v8
	v_mov_b32_dpp v23, v19 row_ror:1 row_mask:0xf bank_mask:0xf
	v_mov_b32_dpp v37, v11 row_shr:2 row_mask:0xf bank_mask:0xf
	v_mov_b32_dpp v20, v21 row_ror:1 row_mask:0xf bank_mask:0xf
	v_mov_b32_dpp v28, v21 row_ror:2 row_mask:0xf bank_mask:0xf
	v_mov_b32_dpp v22, v15 row_shr:1 row_mask:0xf bank_mask:0xf
	v_pk_fma_f32 v[24:25], v[26:27], v[126:127], v[24:25]
	v_mov_b32_dpp v29, v17 row_ror:2 row_mask:0xf bank_mask:0xf
	v_mov_b32_dpp v31, v18 row_ror:1 row_mask:0xf bank_mask:0xf
	v_mov_b32_dpp v35, v18 row_ror:2 row_mask:0xf bank_mask:0xf
	v_mov_b32_dpp v23, v11 row_shr:1 row_mask:0xf bank_mask:0xf
	v_pk_fma_f32 v[18:19], v[76:77], v[36:37], v[72:73]
	v_mov_b32_dpp v28, v13 row_shr:2 row_mask:0xf bank_mask:0xf
	v_mov_b32_dpp v21, v17 row_ror:1 row_mask:0xf bank_mask:0xf
	v_mov_b32_dpp v29, v9 row_shr:2 row_mask:0xf bank_mask:0xf
	v_pk_fma_f32 v[18:19], v[86:87], v[22:23], v[18:19]
	v_mul_f32_e32 v23, 0x3d372713, v24
	v_mov_b32_dpp v20, v13 row_shr:1 row_mask:0xf bank_mask:0xf
	v_mov_b32_dpp v21, v9 row_shr:1 row_mask:0xf bank_mask:0xf
	v_pk_fma_f32 v[16:17], v[74:75], v[28:29], v[70:71]
	v_mul_f32_e32 v23, v24, v23
	v_mov_b32_dpp v34, v14 row_shr:2 row_mask:0xf bank_mask:0xf
	v_pk_fma_f32 v[16:17], v[84:85], v[20:21], v[16:17]
	v_mov_b32_e32 v20, v13
	v_mov_b32_e32 v21, v9
	v_mov_b32_dpp v35, v10 row_shr:2 row_mask:0xf bank_mask:0xf
	v_fma_f32 v23, v24, v23, v24
	v_mov_b32_dpp v30, v14 row_shr:1 row_mask:0xf bank_mask:0xf
	v_pk_fma_f32 v[16:17], v[20:21], v[66:67], v[16:17]
	v_mov_b32_dpp v31, v10 row_shr:1 row_mask:0xf bank_mask:0xf
	v_pk_fma_f32 v[20:21], v[114:115], v[34:35], v[118:119]
	v_mul_f32_e32 v23, 0x3fcc422a, v23
; __device__ __forceinline__ unsigned cvt_pk_bf16(float lo, float hi) { unsigned r; asm volatile("v_cvt_pk_bf16_f32 %0, %1, %2" : "=v"(r) : "v"(lo), "v"(hi)); return r; }
; __device__ __forceinline__ float gelu_t(float x) { const float u = 1.5957691216f * (x + 0.044715f * x * x * x); return x * sigm(u); }
; #define PG8_BAR __builtin_amdgcn_s_barrier()
; __device__ __forceinline__ float dpp_shr1(float old, float src) { return __int_as_float(__builtin_amdgcn_update_dpp(__float_as_int(old), __float_as_int(src), 0x111, 0xf, 0xf, false)); }
; __device__ __forceinline__ float dpp_shr2(float old, float src) { return __int_as_float(__builtin_amdgcn_update_dpp(__float_as_int(old), __float_as_int(src), 0x112, 0xf, 0xf, false)); }
; __device__ __forceinline__ float dpp_ror1(float src) { return __int_as_float(__builtin_amdgcn_update_dpp(0, __float_as_int(src), 0x121, 0xf, 0xf, false)); }
; template <class Epi, class Sched, bool F8 = false>
; __device__ __forceinline__ void gemm_phase(LAS unsigned char* lds, const int lda, const int ldb, const Sched& S, const Epi& E) {
;     ...
;         cur = nxt; cA = nA; cB = nB; ++ui;
;         if (wr == 1) PG8_BAR;
;     __device__ __forceinline__ void operator()(AccT& acc, const Unit& u, int wr, int wc, int fr, int fq) const {
;     ...
;                 for (int m = 0; m < 4; ++m) {
;                     f32x4 c2[2];
; #pragma unroll
;                     for (int bj = 0; bj < 2; ++bj) { const f32x4 cur = acc[ai][bj][m][n]; const f32x4 pv = (m == 0) ? hv[bj] : acc[ai][bj][m == 0 ? 0 : m - 1][n];
; #pragma unroll
;                         for (int j = 0; j < 4; ++j) { const float p1 = dpp_shr1(dpp_ror1(pv[j]), cur[j]), p2 = dpp_shr2(dpp_ror2(pv[j]), cur[j]);
;                             c2[bj][j] = bia[bj][j] + wgt[bj][0][j] * p2 + wgt[bj][1][j] * p1 + wgt[bj][2][j] * cur[j]; } }
;                     u32x2 w; w.x = cvt_pk_bf16(gelu_t(c2[0][0]) * c2[1][0], gelu_t(c2[0][1]) * c2[1][1]); w.y = cvt_pk_bf16(gelu_t(c2[0][2]) * c2[1][2], gelu_t(c2[0][3]) * c2[1][3]);
;                     if (n == 0) pend[ai][m] = w;
;                     else { u32x4 w4; w4.x = pend[ai][m].x; w4.y = pend[ai][m].y; w4.z = w.x; w4.w = w.y;
;                         *(u32x4*)(F + (size_t)(t0 + ai * 128 + wr * 64 + m * 16 + fr) * FF + cg - 4) = w4; }
	v_pk_fma_f32 v[20:21], v[128:129], v[30:31], v[20:21]
	v_mov_b32_e32 v26, v14
	v_mov_b32_e32 v27, v10
	v_mul_f32_e32 v23, 0xbfb8aa3b, v23
	v_pk_fma_f32 v[20:21], v[26:27], v[130:131], v[20:21]
	v_exp_f32_e32 v26, v23
	v_mul_f32_e32 v23, 0x3d372713, v16
	v_mul_f32_e32 v23, v16, v23
	v_fma_f32 v23, v16, v23, v16
	v_add_f32_e32 v26, 1.0, v26
	v_mul_f32_e32 v23, 0x3fcc422a, v23
	v_rcp_f32_e32 v26, v26
	v_mul_f32_e32 v23, 0xbfb8aa3b, v23
	v_mov_b32_e32 v22, v15
	v_exp_f32_e32 v27, v23
	v_mov_b32_e32 v23, v11
	v_pk_fma_f32 v[18:19], v[22:23], v[68:69], v[18:19]
	v_mul_f32_e32 v23, 0x3d372713, v20
	v_mul_f32_e32 v22, v24, v26
	v_mul_f32_e32 v23, v20, v23
	v_mul_f32_e32 v24, 0x3d372713, v18
	v_fma_f32 v23, v20, v23, v20
	v_mul_f32_e32 v24, v18, v24
	v_add_f32_e32 v27, 1.0, v27
	v_mul_f32_e32 v23, 0x3fcc422a, v23
	v_fma_f32 v24, v18, v24, v18
	v_rcp_f32_e32 v27, v27
	v_mul_f32_e32 v23, 0xbfb8aa3b, v23
	v_mul_f32_e32 v24, 0x3fcc422a, v24
	v_exp_f32_e32 v23, v23
	v_mul_f32_e32 v24, 0xbfb8aa3b, v24
	v_exp_f32_e32 v24, v24
	v_mul_f32_e32 v16, v16, v27
	v_mul_f32_e32 v16, v16, v17
	v_add_f32_e32 v17, 1.0, v23
	v_rcp_f32_e32 v17, v17
	v_add_f32_e32 v23, 1.0, v24
	v_rcp_f32_e32 v23, v23
	v_mul_f32_e32 v22, v22, v25
	v_cvt_pk_bf16_f32 v82, v22, v16
	v_mul_f32_e32 v16, v20, v17
	v_mul_f32_e32 v16, v16, v21
	v_mul_f32_e32 v17, v18, v23
	v_mul_f32_e32 v17, v17, v19
	v_cvt_pk_bf16_f32 v83, v16, v17
	v_add_u32_e32 v16, 0xa0, v132
	v_mad_i64_i32 v[16:17], s[6:7], v16, s94, v[32:33]
	v_lshl_add_u64 v[16:17], v[16:17], 0, v[94:95]
	global_store_dwordx4 v[16:17], v[80:83], off nt
	v_mov_b32_dpp v16, v12 row_ror:1 row_mask:0xf bank_mask:0xf
	v_mov_b32_dpp v18, v12 row_ror:2 row_mask:0xf bank_mask:0xf
	v_mov_b32_dpp v19, v8 row_ror:2 row_mask:0xf bank_mask:0xf
	v_mov_b32_dpp v18, v4 row_shr:2 row_mask:0xf bank_mask:0xf
	v_mov_b32_dpp v12, v13 row_ror:1 row_mask:0xf bank_mask:0xf
	v_mov_b32_dpp v20, v13 row_ror:2 row_mask:0xf bank_mask:0xf
	v_mov_b32_dpp v17, v8 row_ror:1 row_mask:0xf bank_mask:0xf
	v_mov_b32_dpp v19, v0 row_shr:2 row_mask:0xf bank_mask:0xf
	v_mov_b32_dpp v21, v9 row_ror:2 row_mask:0xf bank_mask:0xf
	v_mov_b32_dpp v16, v4 row_shr:1 row_mask:0xf bank_mask:0xf
	v_mov_b32_dpp v20, v5 row_shr:2 row_mask:0xf bank_mask:0xf
	v_mov_b32_dpp v17, v0 row_shr:1 row_mask:0xf bank_mask:0xf
	v_pk_fma_f32 v[18:19], v[78:79], v[18:19], v[122:123]
	v_mov_b32_dpp v13, v9 row_ror:1 row_mask:0xf bank_mask:0xf
	v_mov_b32_dpp v21, v1 row_shr:2 row_mask:0xf bank_mask:0xf
	v_mov_b32_dpp v12, v5 row_shr:1 row_mask:0xf bank_mask:0xf
	v_pk_fma_f32 v[16:17], v[124:125], v[16:17], v[18:19]
	v_mov_b32_e32 v18, v4
	v_mov_b32_e32 v19, v0
	v_mov_b32_dpp v13, v1 row_shr:1 row_mask:0xf bank_mask:0xf
	v_pk_fma_f32 v[8:9], v[74:75], v[20:21], v[70:71]
	v_pk_fma_f32 v[16:17], v[18:19], v[126:127], v[16:17]
	v_pk_fma_f32 v[8:9], v[84:85], v[12:13], v[8:9]
	v_mov_b32_e32 v0, v5
	v_mov_b32_dpp v23, v10 row_ror:1 row_mask:0xf bank_mask:0xf
	v_mov_b32_dpp v25, v10 row_ror:2 row_mask:0xf bank_mask:0xf
	v_pk_fma_f32 v[0:1], v[0:1], v[66:67], v[8:9]
	v_mov_b32_dpp v23, v2 row_shr:1 row_mask:0xf bank_mask:0xf
	v_mov_b32_dpp v25, v2 row_shr:2 row_mask:0xf bank_mask:0xf
	v_mov_b32_e32 v9, v2
	v_mul_f32_e32 v2, 0x3d372713, v16
	v_mul_f32_e32 v2, v16, v2
	v_fma_f32 v2, v16, v2, v16
	v_mul_f32_e32 v2, 0x3fcc422a, v2
	v_mov_b32_dpp v22, v14 row_ror:1 row_mask:0xf bank_mask:0xf
	v_mov_b32_dpp v24, v14 row_ror:2 row_mask:0xf bank_mask:0xf
	v_mul_f32_e32 v2, 0xbfb8aa3b, v2
	v_mov_b32_dpp v22, v6 row_shr:1 row_mask:0xf bank_mask:0xf
	v_mov_b32_dpp v24, v6 row_shr:2 row_mask:0xf bank_mask:0xf
	v_mov_b32_e32 v8, v6
	v_exp_f32_e32 v6, v2
	v_mul_f32_e32 v2, 0x3d372713, v0
	v_mul_f32_e32 v2, v0, v2
	v_fma_f32 v2, v0, v2, v0
	v_mul_f32_e32 v2, 0x3fcc422a, v2
	v_mul_f32_e32 v2, 0xbfb8aa3b, v2
	v_exp_f32_e32 v10, v2
	v_mov_b32_dpp v14, v15 row_ror:1 row_mask:0xf bank_mask:0xf
	v_mov_b32_dpp v26, v15 row_ror:2 row_mask:0xf bank_mask:0xf
	v_mov_b32_e32 v2, v7
	v_mov_b32_dpp v14, v7 row_shr:1 row_mask:0xf bank_mask:0xf
	v_mov_b32_dpp v26, v7 row_shr:2 row_mask:0xf bank_mask:0xf
	v_add_f32_e32 v7, 1.0, v10
	v_pk_fma_f32 v[4:5], v[114:115], v[24:25], v[118:119]
	v_mov_b32_dpp v27, v11 row_ror:2 row_mask:0xf bank_mask:0xf
	v_rcp_f32_e32 v7, v7
	v_pk_fma_f32 v[4:5], v[128:129], v[22:23], v[4:5]
	v_mov_b32_dpp v15, v11 row_ror:1 row_mask:0xf bank_mask:0xf
	v_mov_b32_dpp v27, v3 row_shr:2 row_mask:0xf bank_mask:0xf
	v_pk_fma_f32 v[4:5], v[8:9], v[130:131], v[4:5]
	v_mov_b32_dpp v15, v3 row_shr:1 row_mask:0xf bank_mask:0xf
	v_pk_fma_f32 v[8:9], v[76:77], v[26:27], v[72:73]
	v_mul_f32_e32 v0, v0, v7
	v_pk_fma_f32 v[8:9], v[86:87], v[14:15], v[8:9]
	v_mul_f32_e32 v7, 0x3d372713, v4
	v_pk_fma_f32 v[2:3], v[2:3], v[68:69], v[8:9]
	v_mul_f32_e32 v7, v4, v7
	v_mul_f32_e32 v8, 0x3d372713, v2
	v_fma_f32 v7, v4, v7, v4
	v_mul_f32_e32 v8, v2, v8
	v_mul_f32_e32 v7, 0x3fcc422a, v7
	v_fma_f32 v8, v2, v8, v2
	v_mul_f32_e32 v7, 0xbfb8aa3b, v7
	v_mul_f32_e32 v8, 0x3fcc422a, v8
	v_exp_f32_e32 v7, v7
	v_mul_f32_e32 v8, 0xbfb8aa3b, v8
	v_exp_f32_e32 v8, v8
	v_add_f32_e32 v6, 1.0, v6
	v_rcp_f32_e32 v6, v6
	v_mul_f32_e32 v0, v0, v1
	v_add_f32_e32 v1, 1.0, v7
	v_rcp_f32_e32 v1, v1
	v_add_f32_e32 v7, 1.0, v8
	v_rcp_f32_e32 v7, v7
	v_mul_f32_e32 v6, v16, v6
	v_mul_f32_e32 v6, v6, v17
	v_cvt_pk_bf16_f32 v66, v6, v0
	v_mul_f32_e32 v0, v4, v1
	v_mul_f32_e32 v0, v0, v5
	v_mul_f32_e32 v1, v2, v7
	v_mul_f32_e32 v1, v1, v3
	v_cvt_pk_bf16_f32 v67, v0, v1
	v_add_u32_e32 v0, 0xb0, v132
	v_mad_i64_i32 v[0:1], s[6:7], v0, s94, v[32:33]
	v_lshl_add_u64 v[0:1], v[0:1], 0, v[94:95]
	s_andn2_b64 vcc, exec, s[0:1]
	s_mov_b64 s[0:1], -1
	global_store_dwordx4 v[0:1], v[64:67], off nt
	s_cbranch_vccnz .LBB0_774
	s_and_b64 vcc, exec, s[4:5]
	s_cbranch_vccnz .LBB0_773
	s_barrier
	s_branch .LBB0_773
